# rmsnorm row loops (L0 initial + L3 post-mixer): all row/param loads issued together instead of per-group load-wait chains
# speedup vs baseline: 1.0269x; 1.0047x over previous
;     ...
;     for (int r = rbeg + gw; r < nrows; r += nw) {
;         const float* xp = (r < T_LAT) ? xlat + (size_t)r * DM : xctx + (size_t)(r - T_LAT) * DM;
;         const int m = (r < T_LAT) ? (r >> 12) : 8;
;         const float* mv = p.modv + ((size_t)layer * 9 + m) * 6144 + shift_i * 1024;
;         f32x4 v[4];
;         float ss = 0.f;
; #pragma unroll
;         for (int i = 0; i < 4; ++i) {
;             v[i] = *reinterpret_cast<const f32x4*>(xp + (i * 64 + lane) * 4);
;             ss += v[i][0] * v[i][0] + v[i][1] * v[i][1] + v[i][2] * v[i][2] + v[i][3] * v[i][3];
;         }
; #pragma unroll
;         for (int o = 32; o >= 1; o >>= 1) ss += __shfl_xor(ss, o);
;         const float rstd = rsqrtf(ss * (1.0f / 1024.0f) + EPSV);
;         bf16_t* hp = p.hbuf + (size_t)r * DM;
; #pragma unroll
;         for (int i = 0; i < 4; ++i) {
;             const int col = (i * 64 + lane) * 4;
;             f32x4 gg = *reinterpret_cast<const f32x4*>(g + col);
;             f32x4 sh = *reinterpret_cast<const f32x4*>(mv + col);
;             f32x4 sc = *reinterpret_cast<const f32x4*>(mv + 1024 + col);
;             float o0 = v[i][0] * rstd * gg[0] * (1.f + sc[0]) + sh[0];
;             float o1 = v[i][1] * rstd * gg[1] * (1.f + sc[1]) + sh[1];
;             float o2 = v[i][2] * rstd * gg[2] * (1.f + sc[2]) + sh[2];
;             float o3 = v[i][3] * rstd * gg[3] * (1.f + sc[3]) + sh[3];
;             u32x2 o = {pack2(o0, o1), pack2(o2, o3)};
;             *reinterpret_cast<u32x2*>(hp + col) = o;
;         }
;     }
.LBB0_77:
	s_or_b64 exec, exec, s[14:15]
	v_lshl_add_u64 v[20:21], v[20:21], 0, v[10:11]
	global_load_dwordx4 v[28:31], v[20:21], off
	global_load_dwordx4 v[32:35], v[20:21], off offset:1024
	global_load_dwordx4 v[36:39], v[20:21], off offset:2048
	global_load_dwordx4 v[40:43], v[20:21], off offset:3072
	v_min_i32_e32 v20, 0x8000, v2
	v_ashrrev_i32_e32 v20, 12, v20
	v_readlane_b32 s44, v254, 6
	v_mul_hi_i32_i24_e32 v21, 0x6000, v20
	v_mul_i32_i24_e32 v20, 0x6000, v20
	v_readlane_b32 s50, v254, 12
	v_readlane_b32 s51, v254, 13
	v_lshlrev_b64 v[18:19], 11, v[18:19]
	v_lshl_add_u64 v[2:3], v[2:3], 0, s[38:39]
	v_lshl_add_u64 v[20:21], s[50:51], 0, v[20:21]
	v_lshl_add_u64 v[56:57], v[20:21], 0, s[90:91]
	v_lshl_add_u64 v[44:45], v[56:57], 0, v[10:11]
	global_load_dwordx4 v[44:47], v[44:45], off
	s_nop 0
	global_load_dwordx4 v[48:51], v[4:5], off
	v_lshl_add_u64 v[58:59], v[20:21], 0, v[10:11]
	global_load_dwordx4 v[52:55], v[58:59], off
	global_load_dwordx4 v[192:195], v[4:5], off offset:1024
	global_load_dwordx4 v[196:199], v[4:5], off offset:2048
	global_load_dwordx4 v[200:203], v[4:5], off offset:3072
	v_lshl_add_u64 v[228:229], v[56:57], 0, v[12:13]
	global_load_dwordx4 v[204:207], v[228:229], off
	v_lshl_add_u64 v[228:229], v[56:57], 0, v[14:15]
	global_load_dwordx4 v[208:211], v[228:229], off
	v_lshl_add_u64 v[228:229], v[56:57], 0, v[16:17]
	global_load_dwordx4 v[212:215], v[228:229], off
	global_load_dwordx4 v[216:219], v[58:59], off offset:1024
	global_load_dwordx4 v[220:223], v[58:59], off offset:2048
	global_load_dwordx4 v[224:227], v[58:59], off offset:3072
	v_lshl_add_u64 v[8:9], v[8:9], 0, s[52:53]
	v_readlane_b32 s45, v254, 7
	v_readlane_b32 s46, v254, 8
	v_readlane_b32 s47, v254, 9
	v_readlane_b32 s48, v254, 10
	v_readlane_b32 s49, v254, 11
	s_waitcnt vmcnt(12)
	v_mov_b32_e32 v60, v29
	v_mov_b32_e32 v61, v33
	v_mov_b32_e32 v20, v28
	v_mov_b32_e32 v21, v32
	v_mov_b32_e32 v68, v37
	v_mov_b32_e32 v69, v41
	v_pk_mul_f32 v[60:61], v[60:61], v[60:61]
	v_mov_b32_e32 v62, v30
	v_mov_b32_e32 v63, v34
	v_mov_b32_e32 v66, v36
	v_mov_b32_e32 v67, v40
	v_pk_mul_f32 v[68:69], v[68:69], v[68:69]
	v_pk_fma_f32 v[20:21], v[20:21], v[20:21], v[60:61]
	v_mov_b32_e32 v64, v31
	v_mov_b32_e32 v65, v35
	v_mov_b32_e32 v70, v38
	v_mov_b32_e32 v71, v42
	v_pk_fma_f32 v[60:61], v[66:67], v[66:67], v[68:69]
	v_pk_fma_f32 v[20:21], v[62:63], v[62:63], v[20:21]
	v_mov_b32_e32 v72, v39
	v_mov_b32_e32 v73, v43
	v_pk_fma_f32 v[60:61], v[70:71], v[70:71], v[60:61]
	v_pk_fma_f32 v[20:21], v[64:65], v[64:65], v[20:21]
	v_pk_fma_f32 v[60:61], v[72:73], v[72:73], v[60:61]
	v_add_f32_e32 v20, v20, v21
	v_add_f32_e32 v20, v20, v60
	v_add_f32_e32 v20, v20, v61
	ds_bpermute_b32 v21, v1, v20
	v_lshl_add_u64 v[60:61], v[6:7], 0, v[18:19]
	v_lshl_add_u64 v[62:63], v[56:57], 0, v[12:13]
	s_waitcnt lgkmcnt(0)
	v_add_f32_e32 v20, v20, v21
	ds_bpermute_b32 v21, v22, v20
	s_waitcnt lgkmcnt(0)
	v_add_f32_e32 v20, v20, v21
	ds_bpermute_b32 v21, v23, v20
	s_waitcnt lgkmcnt(0)
	v_add_f32_e32 v20, v20, v21
	ds_bpermute_b32 v21, v24, v20
	s_waitcnt lgkmcnt(0)
	v_add_f32_e32 v20, v20, v21
	ds_bpermute_b32 v21, v25, v20
	s_waitcnt lgkmcnt(0)
	v_add_f32_e32 v20, v20, v21
	ds_bpermute_b32 v21, v26, v20
	s_waitcnt lgkmcnt(0)
	v_add_f32_e32 v18, v20, v21
	v_fmamk_f32 v18, v18, 0x3a800000, v177
	v_mul_f32_e32 v19, 0x4b800000, v18
	v_cmp_gt_f32_e32 vcc, s93, v18
	s_waitcnt vmcnt(0)
	v_pk_add_f32 v[20:21], v[46:47], 1.0 op_sel_hi:[1,0]
	v_cndmask_b32_e32 v18, v18, v19, vcc
	v_rsq_f32_e32 v27, v18
	v_pk_add_f32 v[18:19], v[44:45], 1.0 op_sel_hi:[1,0]
	v_mul_f32_e32 v44, 0x45800000, v27
	v_cndmask_b32_e32 v64, v27, v44, vcc
	v_pk_mul_f32 v[28:29], v[28:29], v[64:65] op_sel_hi:[1,0]
	v_pk_mul_f32 v[30:31], v[30:31], v[64:65] op_sel_hi:[1,0]
	v_pk_mul_f32 v[28:29], v[48:49], v[28:29]
	v_pk_mul_f32 v[30:31], v[50:51], v[30:31]
	v_pk_fma_f32 v[18:19], v[18:19], v[28:29], v[52:53]
	v_pk_fma_f32 v[20:21], v[20:21], v[30:31], v[54:55]
	v_cvt_pk_bf16_f32 v18, v18, v19
	v_cvt_pk_bf16_f32 v19, v20, v21
	global_store_dwordx2 v[60:61], v[18:19], off
	s_nop 0
	v_pk_mul_f32 v[32:33], v[32:33], v[64:65] op_sel_hi:[1,0]
	v_pk_mul_f32 v[34:35], v[34:35], v[64:65] op_sel_hi:[1,0]
	v_lshl_add_u64 v[48:49], v[56:57], 0, v[14:15]
	v_pk_mul_f32 v[36:37], v[36:37], v[64:65] op_sel_hi:[1,0]
	v_pk_mul_f32 v[38:39], v[38:39], v[64:65] op_sel_hi:[1,0]
	v_cmp_lt_i32_e32 vcc, s94, v2
	s_or_b64 s[12:13], vcc, s[12:13]
	v_pk_mul_f32 v[18:19], v[192:193], v[32:33]
	v_pk_add_f32 v[28:29], v[204:205], 1.0 op_sel_hi:[1,0]
	v_pk_mul_f32 v[20:21], v[194:195], v[34:35]
	v_pk_add_f32 v[30:31], v[206:207], 1.0 op_sel_hi:[1,0]
	v_pk_fma_f32 v[18:19], v[28:29], v[18:19], v[216:217]
	v_pk_fma_f32 v[20:21], v[30:31], v[20:21], v[218:219]
	v_cvt_pk_bf16_f32 v18, v18, v19
	v_cvt_pk_bf16_f32 v19, v20, v21
	global_store_dwordx2 v[60:61], v[18:19], off offset:512
	s_nop 0
	v_lshl_add_u64 v[44:45], v[56:57], 0, v[16:17]
	v_pk_mul_f32 v[18:19], v[196:197], v[36:37]
	v_pk_add_f32 v[28:29], v[208:209], 1.0 op_sel_hi:[1,0]
	v_pk_mul_f32 v[20:21], v[198:199], v[38:39]
	v_pk_add_f32 v[30:31], v[210:211], 1.0 op_sel_hi:[1,0]
	v_pk_fma_f32 v[18:19], v[28:29], v[18:19], v[220:221]
	v_pk_fma_f32 v[20:21], v[30:31], v[20:21], v[222:223]
	v_cvt_pk_bf16_f32 v18, v18, v19
	v_cvt_pk_bf16_f32 v19, v20, v21
	global_store_dwordx2 v[60:61], v[18:19], off offset:1024
	s_nop 0
	v_pk_mul_f32 v[36:37], v[40:41], v[64:65] op_sel_hi:[1,0]
	v_pk_mul_f32 v[38:39], v[42:43], v[64:65] op_sel_hi:[1,0]
	v_pk_mul_f32 v[18:19], v[36:37], v[200:201]
	v_pk_add_f32 v[28:29], v[212:213], 1.0 op_sel_hi:[1,0]
	v_pk_mul_f32 v[20:21], v[38:39], v[202:203]
	v_pk_add_f32 v[30:31], v[214:215], 1.0 op_sel_hi:[1,0]
	v_pk_fma_f32 v[18:19], v[18:19], v[28:29], v[224:225]
	v_pk_fma_f32 v[20:21], v[20:21], v[30:31], v[226:227]
	v_cvt_pk_bf16_f32 v18, v18, v19
	v_cvt_pk_bf16_f32 v19, v20, v21
	global_store_dwordx2 v[60:61], v[18:19], off offset:1536
	s_andn2_b64 exec, exec, s[12:13]
	s_cbranch_execz .LBB0_80

;     ...
;     for (int r = rbeg + gw; r < nrows; r += nw) {
;         const float* xp = (r < T_LAT) ? xlat + (size_t)r * DM : xctx + (size_t)(r - T_LAT) * DM;
;         const int m = (r < T_LAT) ? (r >> 12) : 8;
;         const float* mv = p.modv + ((size_t)layer * 9 + m) * 6144 + shift_i * 1024;
;         f32x4 v[4];
;         float ss = 0.f;
; #pragma unroll
;         for (int i = 0; i < 4; ++i) {
;             v[i] = *reinterpret_cast<const f32x4*>(xp + (i * 64 + lane) * 4);
;             ss += v[i][0] * v[i][0] + v[i][1] * v[i][1] + v[i][2] * v[i][2] + v[i][3] * v[i][3];
;         }
; #pragma unroll
;         for (int o = 32; o >= 1; o >>= 1) ss += __shfl_xor(ss, o);
;         const float rstd = rsqrtf(ss * (1.0f / 1024.0f) + EPSV);
;         bf16_t* hp = p.hbuf + (size_t)r * DM;
; #pragma unroll
;         for (int i = 0; i < 4; ++i) {
;             const int col = (i * 64 + lane) * 4;
;             f32x4 gg = *reinterpret_cast<const f32x4*>(g + col);
;             f32x4 sh = *reinterpret_cast<const f32x4*>(mv + col);
;             f32x4 sc = *reinterpret_cast<const f32x4*>(mv + 1024 + col);
;             float o0 = v[i][0] * rstd * gg[0] * (1.f + sc[0]) + sh[0];
;             float o1 = v[i][1] * rstd * gg[1] * (1.f + sc[1]) + sh[1];
;             float o2 = v[i][2] * rstd * gg[2] * (1.f + sc[2]) + sh[2];
;             float o3 = v[i][3] * rstd * gg[3] * (1.f + sc[3]) + sh[3];
;             u32x2 o = {pack2(o0, o1), pack2(o2, o3)};
;             *reinterpret_cast<u32x2*>(hp + col) = o;
;         }
;     }
.LBB0_1323:
	s_or_b64 exec, exec, s[14:15]
	v_mov_b32_e32 v27, v0
	v_mov_b32_e32 v29, v0
	v_mov_b32_e32 v31, v0
	v_mov_b32_e32 v33, v0
	v_lshl_add_u64 v[2:3], v[2:3], 0, v[26:27]
	global_load_dwordx4 v[14:17], v[2:3], off
	global_load_dwordx4 v[10:13], v[2:3], off offset:1024
	global_load_dwordx4 v[6:9], v[2:3], off offset:2048
	global_load_dwordx4 v[192:195], v[2:3], off offset:3072
	v_min_i32_e32 v196, 0x8000, v18
	v_ashrrev_i32_e32 v196, 12, v196
	v_readlane_b32 s60, v254, 6
	v_ashrrev_i32_e32 v197, 31, v196
	v_readlane_b32 s66, v254, 12
	v_readlane_b32 s67, v254, 13
	v_lshl_add_u64 v[196:197], v[196:197], 0, s[20:21]
	s_movk_i32 s4, 0x6000
	v_mov_b64_e32 v[198:199], s[66:67]
	v_mad_u64_u32 v[38:39], s[0:1], v196, s4, v[198:199]
	v_mad_i32_i24 v39, v197, s4, v39
	s_mov_b64 s[0:1], 0x3000
	v_lshlrev_b64 v[58:59], 11, v[40:41]
	v_lshl_add_u64 v[18:19], v[18:19], 0, s[38:39]
	v_readlane_b32 s61, v254, 7
	v_readlane_b32 s62, v254, 8
	v_readlane_b32 s63, v254, 9
	v_readlane_b32 s64, v254, 10
	v_readlane_b32 s65, v254, 11
	v_lshl_add_u64 v[36:37], v[38:39], 0, s[0:1]
	s_mov_b64 s[0:1], 0x4000
	v_lshl_add_u64 v[40:41], v[38:39], 0, s[0:1]
	v_lshl_add_u64 v[196:197], v[36:37], 0, v[26:27]
	v_lshl_add_u64 v[198:199], v[40:41], 0, v[26:27]
	global_load_dwordx4 v[200:203], v[196:197], off
	global_load_dwordx4 v[216:219], v[198:199], off
	v_lshl_add_u64 v[196:197], v[36:37], 0, v[28:29]
	v_lshl_add_u64 v[198:199], v[40:41], 0, v[28:29]
	global_load_dwordx4 v[204:207], v[196:197], off
	global_load_dwordx4 v[220:223], v[198:199], off
	v_lshl_add_u64 v[196:197], v[36:37], 0, v[30:31]
	v_lshl_add_u64 v[198:199], v[40:41], 0, v[30:31]
	global_load_dwordx4 v[208:211], v[196:197], off
	global_load_dwordx4 v[224:227], v[198:199], off
	v_lshl_add_u64 v[196:197], v[36:37], 0, v[32:33]
	v_lshl_add_u64 v[198:199], v[40:41], 0, v[32:33]
	global_load_dwordx4 v[212:215], v[196:197], off
	global_load_dwordx4 v[228:231], v[198:199], off
	global_load_dwordx4 v[232:235], v[20:21], off
	global_load_dwordx4 v[236:239], v[20:21], off offset:1024
	global_load_dwordx4 v[240:243], v[20:21], off offset:2048
	global_load_dwordx4 v[244:247], v[20:21], off offset:3072
	v_readlane_b32 s0, v255, 9
	v_readlane_b32 s1, v255, 10
	s_waitcnt vmcnt(12)
	v_mov_b32_e32 v198, v15
	v_mov_b32_e32 v199, v11
	v_mov_b32_e32 v196, v14
	v_mov_b32_e32 v197, v10
	v_pk_mul_f32 v[198:199], v[198:199], v[198:199]
	s_nop 0
	v_pk_fma_f32 v[196:197], v[196:197], v[196:197], v[198:199]
	v_mov_b32_e32 v198, v16
	v_mov_b32_e32 v199, v12
	v_pk_fma_f32 v[196:197], v[198:199], v[198:199], v[196:197]
	v_mov_b32_e32 v198, v17
	v_mov_b32_e32 v199, v13
	v_pk_fma_f32 v[36:37], v[198:199], v[198:199], v[196:197]
	v_add_f32_e32 v29, v36, v37
	v_mov_b32_e32 v48, v7
	v_mov_b32_e32 v49, v193
	v_mov_b32_e32 v46, v6
	v_mov_b32_e32 v47, v192
	v_pk_mul_f32 v[48:49], v[48:49], v[48:49]
	v_lshl_add_u64 v[24:25], v[24:25], 0, s[0:1]
	v_pk_fma_f32 v[46:47], v[46:47], v[46:47], v[48:49]
	v_mov_b32_e32 v48, v8
	v_mov_b32_e32 v49, v194
	v_pk_fma_f32 v[46:47], v[48:49], v[48:49], v[46:47]
	v_mov_b32_e32 v48, v9
	v_mov_b32_e32 v49, v195
	v_pk_fma_f32 v[46:47], v[48:49], v[48:49], v[46:47]
	s_nop 0
	v_add_f32_e32 v29, v29, v46
	v_add_f32_e32 v29, v29, v47
	ds_bpermute_b32 v31, v1, v29
	v_readlane_b32 s0, v255, 34
	s_waitcnt lgkmcnt(0)
	v_add_f32_e32 v29, v29, v31
	ds_bpermute_b32 v31, v35, v29
	s_waitcnt lgkmcnt(0)
	v_add_f32_e32 v29, v29, v31
	ds_bpermute_b32 v31, v42, v29
	s_waitcnt lgkmcnt(0)
	v_add_f32_e32 v29, v29, v31
	ds_bpermute_b32 v31, v43, v29
	s_waitcnt lgkmcnt(0)
	v_add_f32_e32 v29, v29, v31
	ds_bpermute_b32 v31, v44, v29
	s_waitcnt lgkmcnt(0)
	v_add_f32_e32 v29, v29, v31
	ds_bpermute_b32 v31, v45, v29
	s_waitcnt lgkmcnt(0)
	v_add_f32_e32 v29, v29, v31
	v_fmamk_f32 v29, v29, 0x3a800000, v177
	v_cmp_gt_f32_e32 vcc, s93, v29
	v_mul_f32_e32 v31, 0x4b800000, v29
	s_nop 0
	v_cndmask_b32_e32 v29, v29, v31, vcc
	v_rsq_f32_e32 v29, v29
	s_nop 0
	v_mul_f32_e32 v31, 0x45800000, v29
	v_cndmask_b32_e32 v34, v29, v31, vcc
	v_pk_mul_f32 v[14:15], v[14:15], v[34:35] op_sel_hi:[1,0]
	v_pk_mul_f32 v[16:17], v[16:17], v[34:35] op_sel_hi:[1,0]
	v_pk_mul_f32 v[10:11], v[10:11], v[34:35] op_sel_hi:[1,0]
	v_pk_mul_f32 v[12:13], v[12:13], v[34:35] op_sel_hi:[1,0]
	v_pk_mul_f32 v[6:7], v[6:7], v[34:35] op_sel_hi:[1,0]
	v_pk_mul_f32 v[8:9], v[8:9], v[34:35] op_sel_hi:[1,0]
	v_pk_mul_f32 v[192:193], v[192:193], v[34:35] op_sel_hi:[1,0]
	v_pk_mul_f32 v[194:195], v[194:195], v[34:35] op_sel_hi:[1,0]
	v_cmp_le_i32_e32 vcc, s0, v18
	s_or_b64 s[12:13], vcc, s[12:13]
	v_lshl_add_u64 v[38:39], v[22:23], 0, v[58:59]
	s_waitcnt vmcnt(0)
	v_pk_mul_f32 v[14:15], v[232:233], v[14:15]
	v_pk_add_f32 v[196:197], v[216:217], 1.0 op_sel_hi:[1,0]
	v_pk_mul_f32 v[16:17], v[234:235], v[16:17]
	v_pk_fma_f32 v[14:15], v[196:197], v[14:15], v[200:201]
	v_pk_add_f32 v[196:197], v[218:219], 1.0 op_sel_hi:[1,0]
	v_cvt_pk_bf16_f32 v14, v14, v15
	v_pk_fma_f32 v[16:17], v[196:197], v[16:17], v[202:203]
	s_nop 0
	v_cvt_pk_bf16_f32 v15, v16, v17
	global_store_dwordx2 v[38:39], v[14:15], off
	v_pk_mul_f32 v[10:11], v[236:237], v[10:11]
	v_pk_add_f32 v[196:197], v[220:221], 1.0 op_sel_hi:[1,0]
	v_pk_mul_f32 v[12:13], v[238:239], v[12:13]
	v_pk_fma_f32 v[10:11], v[196:197], v[10:11], v[204:205]
	v_pk_add_f32 v[196:197], v[222:223], 1.0 op_sel_hi:[1,0]
	v_cvt_pk_bf16_f32 v10, v10, v11
	v_pk_fma_f32 v[12:13], v[196:197], v[12:13], v[206:207]
	s_nop 0
	v_cvt_pk_bf16_f32 v11, v12, v13
	global_store_dwordx2 v[38:39], v[10:11], off offset:512
	v_pk_mul_f32 v[6:7], v[240:241], v[6:7]
	v_pk_add_f32 v[196:197], v[224:225], 1.0 op_sel_hi:[1,0]
	v_pk_mul_f32 v[8:9], v[242:243], v[8:9]
	v_pk_fma_f32 v[6:7], v[196:197], v[6:7], v[208:209]
	v_pk_add_f32 v[196:197], v[226:227], 1.0 op_sel_hi:[1,0]
	v_cvt_pk_bf16_f32 v6, v6, v7
	v_pk_fma_f32 v[8:9], v[196:197], v[8:9], v[210:211]
	s_nop 0
	v_cvt_pk_bf16_f32 v7, v8, v9
	global_store_dwordx2 v[38:39], v[6:7], off offset:1024
	v_pk_mul_f32 v[192:193], v[244:245], v[192:193]
	v_pk_add_f32 v[196:197], v[228:229], 1.0 op_sel_hi:[1,0]
	v_pk_mul_f32 v[194:195], v[246:247], v[194:195]
	v_pk_fma_f32 v[192:193], v[196:197], v[192:193], v[212:213]
	v_pk_add_f32 v[196:197], v[230:231], 1.0 op_sel_hi:[1,0]
	v_cvt_pk_bf16_f32 v192, v192, v193
	v_pk_fma_f32 v[194:195], v[196:197], v[194:195], v[214:215]
	s_nop 0
	v_cvt_pk_bf16_f32 v193, v194, v195
	global_store_dwordx2 v[38:39], v[192:193], off offset:1536
	s_andn2_b64 exec, exec, s[12:13]
	s_cbranch_execz .LBB0_1326
